# LDS-DMA addresses in the P6 (gate/up) and P7 (down) K-loops as SGPR base + 32-bit VGPR offset (saddr form): the 16 v_lshl_add_u64 per iteration removed
# speedup vs baseline: 1.0148x; 1.0077x over previous
.LBB0_1238:
	s_add_i32 s74, s38, 2
	s_add_u32 s39, s36, 0xfff80080
	s_addc_u32 s40, s37, -1
	s_cmp_eq_u32 s71, s38
	s_cselect_b32 s41, s67, s40
	s_cselect_b32 s40, s68, s39
	v_add_u32_e32 v152, s55, v177
	v_add_u32_e32 v168, s60, v177
	ds_read_b128 v[140:143], v152
	ds_read_b128 v[144:147], v152 offset:1024
	ds_read_b128 v[148:151], v152 offset:2048
	ds_read_b128 v[152:155], v152 offset:3072
	ds_read_b128 v[156:159], v168
	ds_read_b128 v[160:163], v168 offset:1024
	ds_read_b128 v[164:167], v168 offset:2048
	ds_read_b128 v[168:171], v168 offset:3072
	s_cselect_b32 s38, s70, s72
	s_cselect_b32 s39, s69, s73
	s_add_i32 m0, s45, 0xc000
	ds_read_b128 v[180:183], v178
	ds_read_b128 v[184:187], v178 offset:1024
	ds_read_b128 v[188:191], v178 offset:2048
	ds_read_b128 v[192:195], v178 offset:3072
	ds_read_b128 v[196:199], v178 offset:4096
	ds_read_b128 v[200:203], v178 offset:5120
	ds_read_b128 v[204:207], v178 offset:6144
	ds_read_b128 v[208:211], v178 offset:7168
	global_load_lds_dwordx4 v136, s[36:37]
	s_add_i32 m0, s45, 0xe000
	s_nop 0
	global_load_lds_dwordx4 v138, s[36:37]
	s_waitcnt vmcnt(8)
	s_waitcnt lgkmcnt(0)
	s_barrier
	s_setprio 1
	s_waitcnt lgkmcnt(0)
	v_mfma_i32_16x16x64_i8 v[124:127], v[140:143], v[180:183], v[124:127]
	v_mfma_i32_16x16x64_i8 v[120:123], v[148:151], v[180:183], v[120:123]
	v_mfma_i32_16x16x64_i8 v[116:119], v[140:143], v[188:191], v[116:119]
	v_mfma_i32_16x16x64_i8 v[112:115], v[148:151], v[188:191], v[112:115]
	v_mfma_i32_16x16x64_i8 v[104:107], v[140:143], v[196:199], v[104:107]
	v_mfma_i32_16x16x64_i8 v[96:99], v[148:151], v[196:199], v[96:99]
	v_mfma_i32_16x16x64_i8 v[88:91], v[140:143], v[204:207], v[88:91]
	v_mfma_i32_16x16x64_i8 v[80:83], v[148:151], v[204:207], v[80:83]
	v_mfma_i32_16x16x64_i8 v[124:127], v[144:147], v[184:187], v[124:127]
	v_mfma_i32_16x16x64_i8 v[120:123], v[152:155], v[184:187], v[120:123]
	v_mfma_i32_16x16x64_i8 v[116:119], v[144:147], v[192:195], v[116:119]
	v_mfma_i32_16x16x64_i8 v[112:115], v[152:155], v[192:195], v[112:115]
	v_mfma_i32_16x16x64_i8 v[104:107], v[144:147], v[200:203], v[104:107]
	v_mfma_i32_16x16x64_i8 v[96:99], v[152:155], v[200:203], v[96:99]
	v_mfma_i32_16x16x64_i8 v[88:91], v[144:147], v[208:211], v[88:91]
	v_mfma_i32_16x16x64_i8 v[80:83], v[152:155], v[208:211], v[80:83]
	s_setprio 0
	s_setprio 1
	v_mfma_i32_16x16x64_i8 v[108:111], v[156:159], v[180:183], v[108:111]
	v_mfma_i32_16x16x64_i8 v[100:103], v[164:167], v[180:183], v[100:103]
	v_mfma_i32_16x16x64_i8 v[92:95], v[156:159], v[188:191], v[92:95]
	v_mfma_i32_16x16x64_i8 v[84:87], v[164:167], v[188:191], v[84:87]
	v_mfma_i32_16x16x64_i8 v[76:79], v[156:159], v[196:199], v[76:79]
	v_mfma_i32_16x16x64_i8 v[72:75], v[164:167], v[196:199], v[72:75]
	v_mfma_i32_16x16x64_i8 v[68:71], v[156:159], v[204:207], v[68:71]
	v_mfma_i32_16x16x64_i8 v[64:67], v[164:167], v[204:207], v[64:67]
	v_mfma_i32_16x16x64_i8 v[108:111], v[160:163], v[184:187], v[108:111]
	v_mfma_i32_16x16x64_i8 v[100:103], v[168:171], v[184:187], v[100:103]
	v_mfma_i32_16x16x64_i8 v[92:95], v[160:163], v[192:195], v[92:95]
	v_mfma_i32_16x16x64_i8 v[84:87], v[168:171], v[192:195], v[84:87]
	v_mfma_i32_16x16x64_i8 v[76:79], v[160:163], v[200:203], v[76:79]
	v_mfma_i32_16x16x64_i8 v[72:75], v[168:171], v[200:203], v[72:75]
	v_mfma_i32_16x16x64_i8 v[68:71], v[160:163], v[208:211], v[68:71]
	v_mfma_i32_16x16x64_i8 v[64:67], v[168:171], v[208:211], v[64:67]
	s_setprio 0
	s_barrier
	s_add_i32 s75, s55, s42
	s_mov_b32 m0, s75
	ds_read_b128 v[180:183], v178 offset:16384
	ds_read_b128 v[184:187], v178 offset:17408
	ds_read_b128 v[188:191], v178 offset:18432
	ds_read_b128 v[192:195], v178 offset:19456
	ds_read_b128 v[196:199], v178 offset:20480
	ds_read_b128 v[200:203], v178 offset:21504
	ds_read_b128 v[204:207], v178 offset:22528
	ds_read_b128 v[208:211], v178 offset:23552
	global_load_lds_dwordx4 v130, s[38:39]
	s_add_i32 m0, s75, 0x2000
	s_add_u32 s76, s38, 0x80000
	s_addc_u32 s77, s39, 0
	s_add_i32 s75, s60, s42
	global_load_lds_dwordx4 v134, s[38:39]
	s_mov_b32 m0, s75
	s_nop 0
	global_load_lds_dwordx4 v130, s[76:77]
	s_add_i32 m0, s75, 0x2000
	s_nop 0
	global_load_lds_dwordx4 v134, s[76:77]
	s_mov_b32 m0, s45
	s_nop 0
	global_load_lds_dwordx4 v128, s[40:41]
	s_mov_b32 m0, s46
	s_nop 0
	global_load_lds_dwordx4 v132, s[40:41]
	s_waitcnt vmcnt(8)
	s_waitcnt lgkmcnt(0)
	s_barrier
	s_setprio 1
	s_waitcnt lgkmcnt(0)
	v_mfma_i32_16x16x64_i8 v[60:63], v[140:143], v[180:183], v[60:63]
	v_mfma_i32_16x16x64_i8 v[56:59], v[148:151], v[180:183], v[56:59]
	v_mfma_i32_16x16x64_i8 v[52:55], v[140:143], v[188:191], v[52:55]
	v_mfma_i32_16x16x64_i8 v[48:51], v[148:151], v[188:191], v[48:51]
	v_mfma_i32_16x16x64_i8 v[40:43], v[140:143], v[196:199], v[40:43]
	v_mfma_i32_16x16x64_i8 v[32:35], v[148:151], v[196:199], v[32:35]
	v_mfma_i32_16x16x64_i8 v[24:27], v[140:143], v[204:207], v[24:27]
	v_mfma_i32_16x16x64_i8 v[16:19], v[148:151], v[204:207], v[16:19]
	v_mfma_i32_16x16x64_i8 v[60:63], v[144:147], v[184:187], v[60:63]
	v_mfma_i32_16x16x64_i8 v[56:59], v[152:155], v[184:187], v[56:59]
	v_mfma_i32_16x16x64_i8 v[52:55], v[144:147], v[192:195], v[52:55]
	v_mfma_i32_16x16x64_i8 v[48:51], v[152:155], v[192:195], v[48:51]
	v_mfma_i32_16x16x64_i8 v[40:43], v[144:147], v[200:203], v[40:43]
	v_mfma_i32_16x16x64_i8 v[32:35], v[152:155], v[200:203], v[32:35]
	v_mfma_i32_16x16x64_i8 v[24:27], v[144:147], v[208:211], v[24:27]
	v_mfma_i32_16x16x64_i8 v[16:19], v[152:155], v[208:211], v[16:19]
	s_setprio 0
	s_setprio 1
	v_mfma_i32_16x16x64_i8 v[44:47], v[156:159], v[180:183], v[44:47]
	v_mfma_i32_16x16x64_i8 v[36:39], v[164:167], v[180:183], v[36:39]
	v_mfma_i32_16x16x64_i8 v[28:31], v[156:159], v[188:191], v[28:31]
	v_mfma_i32_16x16x64_i8 v[20:23], v[164:167], v[188:191], v[20:23]
	v_mfma_i32_16x16x64_i8 v[12:15], v[156:159], v[196:199], v[12:15]
	v_mfma_i32_16x16x64_i8 v[8:11], v[164:167], v[196:199], v[8:11]
	v_mfma_i32_16x16x64_i8 v[4:7], v[156:159], v[204:207], v[4:7]
	v_mfma_i32_16x16x64_i8 v[0:3], v[164:167], v[204:207], v[0:3]
	v_mfma_i32_16x16x64_i8 v[44:47], v[160:163], v[184:187], v[44:47]
	v_mfma_i32_16x16x64_i8 v[36:39], v[168:171], v[184:187], v[36:39]
	v_mfma_i32_16x16x64_i8 v[28:31], v[160:163], v[192:195], v[28:31]
	v_mfma_i32_16x16x64_i8 v[20:23], v[168:171], v[192:195], v[20:23]
	v_mfma_i32_16x16x64_i8 v[12:15], v[160:163], v[200:203], v[12:15]
	v_mfma_i32_16x16x64_i8 v[8:11], v[168:171], v[200:203], v[8:11]
	v_mfma_i32_16x16x64_i8 v[4:7], v[160:163], v[208:211], v[4:7]
	v_mfma_i32_16x16x64_i8 v[0:3], v[168:171], v[208:211], v[0:3]
	s_setprio 0
	s_barrier
	s_add_i32 s75, 0, 0x18000
	s_add_i32 s76, 0, 0x1c000
	v_add_u32_e32 v152, s75, v177
	v_add_u32_e32 v168, s76, v177
	ds_read_b128 v[140:143], v152
	ds_read_b128 v[144:147], v152 offset:1024
	ds_read_b128 v[148:151], v152 offset:2048
	ds_read_b128 v[152:155], v152 offset:3072
	ds_read_b128 v[156:159], v168
	ds_read_b128 v[160:163], v168 offset:1024
	ds_read_b128 v[164:167], v168 offset:2048
	ds_read_b128 v[168:171], v168 offset:3072
	s_add_u32 s40, s40, 0x80000
	s_addc_u32 s41, s41, 0
	s_mov_b32 m0, s47
	ds_read_b128 v[180:183], v178 offset:32768
	ds_read_b128 v[184:187], v178 offset:33792
	ds_read_b128 v[188:191], v178 offset:34816
	ds_read_b128 v[192:195], v178 offset:35840
	ds_read_b128 v[196:199], v178 offset:36864
	ds_read_b128 v[200:203], v178 offset:37888
	ds_read_b128 v[204:207], v178 offset:38912
	ds_read_b128 v[208:211], v178 offset:39936
	global_load_lds_dwordx4 v128, s[40:41]
	s_mov_b32 m0, s48
	s_nop 0
	global_load_lds_dwordx4 v132, s[40:41]
	s_waitcnt vmcnt(8)
	s_waitcnt lgkmcnt(0)
	s_barrier
	s_setprio 1
	s_waitcnt lgkmcnt(0)
	v_mfma_i32_16x16x64_i8 v[124:127], v[140:143], v[180:183], v[124:127]
	v_mfma_i32_16x16x64_i8 v[120:123], v[148:151], v[180:183], v[120:123]
	v_mfma_i32_16x16x64_i8 v[116:119], v[140:143], v[188:191], v[116:119]
	v_mfma_i32_16x16x64_i8 v[112:115], v[148:151], v[188:191], v[112:115]
	v_mfma_i32_16x16x64_i8 v[104:107], v[140:143], v[196:199], v[104:107]
	v_mfma_i32_16x16x64_i8 v[96:99], v[148:151], v[196:199], v[96:99]
	v_mfma_i32_16x16x64_i8 v[88:91], v[140:143], v[204:207], v[88:91]
	v_mfma_i32_16x16x64_i8 v[80:83], v[148:151], v[204:207], v[80:83]
	v_mfma_i32_16x16x64_i8 v[124:127], v[144:147], v[184:187], v[124:127]
	v_mfma_i32_16x16x64_i8 v[120:123], v[152:155], v[184:187], v[120:123]
	v_mfma_i32_16x16x64_i8 v[116:119], v[144:147], v[192:195], v[116:119]
	v_mfma_i32_16x16x64_i8 v[112:115], v[152:155], v[192:195], v[112:115]
	v_mfma_i32_16x16x64_i8 v[104:107], v[144:147], v[200:203], v[104:107]
	v_mfma_i32_16x16x64_i8 v[96:99], v[152:155], v[200:203], v[96:99]
	v_mfma_i32_16x16x64_i8 v[88:91], v[144:147], v[208:211], v[88:91]
	v_mfma_i32_16x16x64_i8 v[80:83], v[152:155], v[208:211], v[80:83]
	s_setprio 0
	s_setprio 1
	v_mfma_i32_16x16x64_i8 v[108:111], v[156:159], v[180:183], v[108:111]
	v_mfma_i32_16x16x64_i8 v[100:103], v[164:167], v[180:183], v[100:103]
	v_mfma_i32_16x16x64_i8 v[92:95], v[156:159], v[188:191], v[92:95]
	v_mfma_i32_16x16x64_i8 v[84:87], v[164:167], v[188:191], v[84:87]
	v_mfma_i32_16x16x64_i8 v[76:79], v[156:159], v[196:199], v[76:79]
	v_mfma_i32_16x16x64_i8 v[72:75], v[164:167], v[196:199], v[72:75]
	v_mfma_i32_16x16x64_i8 v[68:71], v[156:159], v[204:207], v[68:71]
	v_mfma_i32_16x16x64_i8 v[64:67], v[164:167], v[204:207], v[64:67]
	v_mfma_i32_16x16x64_i8 v[108:111], v[160:163], v[184:187], v[108:111]
	v_mfma_i32_16x16x64_i8 v[100:103], v[168:171], v[184:187], v[100:103]
	v_mfma_i32_16x16x64_i8 v[92:95], v[160:163], v[192:195], v[92:95]
	v_mfma_i32_16x16x64_i8 v[84:87], v[168:171], v[192:195], v[84:87]
	v_mfma_i32_16x16x64_i8 v[76:79], v[160:163], v[200:203], v[76:79]
	v_mfma_i32_16x16x64_i8 v[72:75], v[168:171], v[200:203], v[72:75]
	v_mfma_i32_16x16x64_i8 v[68:71], v[160:163], v[208:211], v[68:71]
	v_mfma_i32_16x16x64_i8 v[64:67], v[168:171], v[208:211], v[64:67]
	s_setprio 0
	s_barrier
	s_add_u32 s98, s38, s20
	s_addc_u32 s99, s39, s21
	s_add_u32 s100, s40, s20
	s_addc_u32 s101, s41, s21
	s_sub_u32 s100, s100, 0x80000
	s_subb_u32 s101, s101, 0
	s_add_i32 s40, s75, s42
	s_mov_b32 m0, s40
	ds_read_b128 v[180:183], v178 offset:49152
	ds_read_b128 v[184:187], v178 offset:50176
	ds_read_b128 v[188:191], v178 offset:51200
	ds_read_b128 v[192:195], v178 offset:52224
	ds_read_b128 v[196:199], v178 offset:53248
	ds_read_b128 v[200:203], v178 offset:54272
	ds_read_b128 v[204:207], v178 offset:55296
	ds_read_b128 v[208:211], v178 offset:56320
	global_load_lds_dwordx4 v130, s[98:99]
	s_add_i32 m0, s40, 0x2000
	s_add_u32 s38, s38, 0x80080
	s_addc_u32 s39, s39, 0
	s_add_i32 s40, s76, s42
	global_load_lds_dwordx4 v134, s[98:99]
	s_mov_b32 m0, s40
	s_nop 0
	global_load_lds_dwordx4 v130, s[38:39]
	s_add_i32 m0, s40, 0x2000
	s_nop 0
	global_load_lds_dwordx4 v134, s[38:39]
	s_mov_b32 m0, s51
	s_nop 0
	global_load_lds_dwordx4 v128, s[100:101]
	s_mov_b32 m0, s52
	s_nop 0
	global_load_lds_dwordx4 v132, s[100:101]
	s_waitcnt vmcnt(8)
	s_waitcnt lgkmcnt(0)
	s_barrier
	s_setprio 1
	s_waitcnt lgkmcnt(0)
	v_mfma_i32_16x16x64_i8 v[60:63], v[140:143], v[180:183], v[60:63]
	v_mfma_i32_16x16x64_i8 v[56:59], v[148:151], v[180:183], v[56:59]
	v_mfma_i32_16x16x64_i8 v[52:55], v[140:143], v[188:191], v[52:55]
	v_mfma_i32_16x16x64_i8 v[48:51], v[148:151], v[188:191], v[48:51]
	v_mfma_i32_16x16x64_i8 v[40:43], v[140:143], v[196:199], v[40:43]
	v_mfma_i32_16x16x64_i8 v[32:35], v[148:151], v[196:199], v[32:35]
	v_mfma_i32_16x16x64_i8 v[24:27], v[140:143], v[204:207], v[24:27]
	v_mfma_i32_16x16x64_i8 v[16:19], v[148:151], v[204:207], v[16:19]
	v_mfma_i32_16x16x64_i8 v[60:63], v[144:147], v[184:187], v[60:63]
	v_mfma_i32_16x16x64_i8 v[56:59], v[152:155], v[184:187], v[56:59]
	v_mfma_i32_16x16x64_i8 v[52:55], v[144:147], v[192:195], v[52:55]
	v_mfma_i32_16x16x64_i8 v[48:51], v[152:155], v[192:195], v[48:51]
	v_mfma_i32_16x16x64_i8 v[40:43], v[144:147], v[200:203], v[40:43]
	v_mfma_i32_16x16x64_i8 v[32:35], v[152:155], v[200:203], v[32:35]
	v_mfma_i32_16x16x64_i8 v[24:27], v[144:147], v[208:211], v[24:27]
	v_mfma_i32_16x16x64_i8 v[16:19], v[152:155], v[208:211], v[16:19]
	s_setprio 0
	s_setprio 1
	v_mfma_i32_16x16x64_i8 v[44:47], v[156:159], v[180:183], v[44:47]
	v_mfma_i32_16x16x64_i8 v[36:39], v[164:167], v[180:183], v[36:39]
	v_mfma_i32_16x16x64_i8 v[28:31], v[156:159], v[188:191], v[28:31]
	v_mfma_i32_16x16x64_i8 v[20:23], v[164:167], v[188:191], v[20:23]
	v_mfma_i32_16x16x64_i8 v[12:15], v[156:159], v[196:199], v[12:15]
	v_mfma_i32_16x16x64_i8 v[8:11], v[164:167], v[196:199], v[8:11]
	v_mfma_i32_16x16x64_i8 v[4:7], v[156:159], v[204:207], v[4:7]
	v_mfma_i32_16x16x64_i8 v[0:3], v[164:167], v[204:207], v[0:3]
	v_mfma_i32_16x16x64_i8 v[44:47], v[160:163], v[184:187], v[44:47]
	v_mfma_i32_16x16x64_i8 v[36:39], v[168:171], v[184:187], v[36:39]
	v_mfma_i32_16x16x64_i8 v[28:31], v[160:163], v[192:195], v[28:31]
	v_mfma_i32_16x16x64_i8 v[20:23], v[168:171], v[192:195], v[20:23]
	v_mfma_i32_16x16x64_i8 v[12:15], v[160:163], v[200:203], v[12:15]
	v_mfma_i32_16x16x64_i8 v[8:11], v[168:171], v[200:203], v[8:11]
	v_mfma_i32_16x16x64_i8 v[4:7], v[160:163], v[208:211], v[4:7]
	v_mfma_i32_16x16x64_i8 v[0:3], v[168:171], v[208:211], v[0:3]
	s_setprio 0
	s_barrier
	s_add_u32 s36, s36, 0x100
	s_addc_u32 s37, s37, 0
	s_add_u32 s72, s72, 0x100
	s_addc_u32 s73, s73, 0
	s_cmp_ge_i32 s74, s8
	s_mov_b32 s38, s74
	s_cbranch_scc0 .LBB0_1238

.Lq_body_L:
	s_add_i32 s74, s38, 2
	s_add_u32 s39, s36, 0xfff80080
	s_addc_u32 s40, s37, -1
	s_cmp_eq_u32 s71, s38
	s_cselect_b32 s41, s67, s40
	s_cselect_b32 s40, s68, s39
	v_add_u32_e32 v152, s55, v177
	v_add_u32_e32 v168, s60, v177
	ds_read_b128 v[140:143], v152
	ds_read_b128 v[144:147], v152 offset:1024
	ds_read_b128 v[148:151], v152 offset:2048
	ds_read_b128 v[152:155], v152 offset:3072
	ds_read_b128 v[156:159], v168
	ds_read_b128 v[160:163], v168 offset:1024
	ds_read_b128 v[164:167], v168 offset:2048
	ds_read_b128 v[168:171], v168 offset:3072
	s_cselect_b32 s38, s70, s72
	s_cselect_b32 s39, s69, s73
	s_add_i32 m0, s45, 0xc000
	ds_read_b128 v[180:183], v178
	ds_read_b128 v[184:187], v178 offset:1024
	ds_read_b128 v[188:191], v178 offset:2048
	ds_read_b128 v[192:195], v178 offset:3072
	ds_read_b128 v[196:199], v178 offset:4096
	ds_read_b128 v[200:203], v178 offset:5120
	ds_read_b128 v[204:207], v178 offset:6144
	ds_read_b128 v[208:211], v178 offset:7168
	global_load_lds_dwordx4 v136, s[36:37]
	s_add_i32 m0, s45, 0xe000
	s_nop 0
	global_load_lds_dwordx4 v138, s[36:37]
	global_load_dwordx4 v[226:229], v223, s[100:101] nt
	s_add_u32 s84, s84, 1
	s_waitcnt vmcnt(9)
	s_waitcnt lgkmcnt(0)
	s_barrier
	s_setprio 1
	s_waitcnt lgkmcnt(0)
	v_mfma_i32_16x16x64_i8 v[124:127], v[140:143], v[180:183], v[124:127]
	v_mfma_i32_16x16x64_i8 v[120:123], v[148:151], v[180:183], v[120:123]
	v_mfma_i32_16x16x64_i8 v[116:119], v[140:143], v[188:191], v[116:119]
	v_mfma_i32_16x16x64_i8 v[112:115], v[148:151], v[188:191], v[112:115]
	v_mfma_i32_16x16x64_i8 v[104:107], v[140:143], v[196:199], v[104:107]
	v_mfma_i32_16x16x64_i8 v[96:99], v[148:151], v[196:199], v[96:99]
	v_mfma_i32_16x16x64_i8 v[88:91], v[140:143], v[204:207], v[88:91]
	v_mfma_i32_16x16x64_i8 v[80:83], v[148:151], v[204:207], v[80:83]
	v_mfma_i32_16x16x64_i8 v[124:127], v[144:147], v[184:187], v[124:127]
	v_mfma_i32_16x16x64_i8 v[120:123], v[152:155], v[184:187], v[120:123]
	v_mfma_i32_16x16x64_i8 v[116:119], v[144:147], v[192:195], v[116:119]
	v_mfma_i32_16x16x64_i8 v[112:115], v[152:155], v[192:195], v[112:115]
	v_mfma_i32_16x16x64_i8 v[104:107], v[144:147], v[200:203], v[104:107]
	v_mfma_i32_16x16x64_i8 v[96:99], v[152:155], v[200:203], v[96:99]
	v_mfma_i32_16x16x64_i8 v[88:91], v[144:147], v[208:211], v[88:91]
	v_mfma_i32_16x16x64_i8 v[80:83], v[152:155], v[208:211], v[80:83]
	s_setprio 0
	s_setprio 1
	v_mfma_i32_16x16x64_i8 v[108:111], v[156:159], v[180:183], v[108:111]
	v_mfma_i32_16x16x64_i8 v[100:103], v[164:167], v[180:183], v[100:103]
	v_mfma_i32_16x16x64_i8 v[92:95], v[156:159], v[188:191], v[92:95]
	v_mfma_i32_16x16x64_i8 v[84:87], v[164:167], v[188:191], v[84:87]
	v_mfma_i32_16x16x64_i8 v[76:79], v[156:159], v[196:199], v[76:79]
	v_mfma_i32_16x16x64_i8 v[72:75], v[164:167], v[196:199], v[72:75]
	v_mfma_i32_16x16x64_i8 v[68:71], v[156:159], v[204:207], v[68:71]
	v_mfma_i32_16x16x64_i8 v[64:67], v[164:167], v[204:207], v[64:67]
	v_mfma_i32_16x16x64_i8 v[108:111], v[160:163], v[184:187], v[108:111]
	v_mfma_i32_16x16x64_i8 v[100:103], v[168:171], v[184:187], v[100:103]
	v_mfma_i32_16x16x64_i8 v[92:95], v[160:163], v[192:195], v[92:95]
	v_mfma_i32_16x16x64_i8 v[84:87], v[168:171], v[192:195], v[84:87]
	v_mfma_i32_16x16x64_i8 v[76:79], v[160:163], v[200:203], v[76:79]
	v_mfma_i32_16x16x64_i8 v[72:75], v[168:171], v[200:203], v[72:75]
	v_mfma_i32_16x16x64_i8 v[68:71], v[160:163], v[208:211], v[68:71]
	v_mfma_i32_16x16x64_i8 v[64:67], v[168:171], v[208:211], v[64:67]
	s_setprio 0
	s_barrier
	s_add_i32 s75, s55, s42
	v_lshl_add_u64 v[172:173], s[38:39], 0, v[130:131]
	s_mov_b32 m0, s75
	ds_read_b128 v[180:183], v178 offset:16384
	ds_read_b128 v[184:187], v178 offset:17408
	ds_read_b128 v[188:191], v178 offset:18432
	ds_read_b128 v[192:195], v178 offset:19456
	ds_read_b128 v[196:199], v178 offset:20480
	ds_read_b128 v[200:203], v178 offset:21504
	ds_read_b128 v[204:207], v178 offset:22528
	ds_read_b128 v[208:211], v178 offset:23552
	global_load_lds_dwordx4 v130, s[38:39]
	s_add_i32 m0, s75, 0x2000
	s_add_u32 s76, s38, 0x80000
	v_lshl_add_u64 v[212:213], s[38:39], 0, v[134:135]
	s_addc_u32 s77, s39, 0
	s_add_i32 s75, s60, s42
	global_load_lds_dwordx4 v134, s[38:39]
	s_mov_b32 m0, s75
	v_lshl_add_u64 v[216:217], s[40:41], 0, v[132:133]
	global_load_lds_dwordx4 v130, s[76:77]
	s_add_i32 m0, s75, 0x2000
	s_nop 0
	global_load_lds_dwordx4 v134, s[76:77]
	v_lshl_add_u64 v[214:215], s[40:41], 0, v[128:129]
	s_mov_b32 m0, s45
	s_nop 0
	global_load_lds_dwordx4 v128, s[40:41]
	s_mov_b32 m0, s46
	s_nop 0
	global_load_lds_dwordx4 v132, s[40:41]
	s_waitcnt vmcnt(9)
	s_waitcnt lgkmcnt(0)
	s_barrier
	s_setprio 1
	s_waitcnt lgkmcnt(0)
	v_mfma_i32_16x16x64_i8 v[60:63], v[140:143], v[180:183], v[60:63]
	v_mfma_i32_16x16x64_i8 v[56:59], v[148:151], v[180:183], v[56:59]
	v_mfma_i32_16x16x64_i8 v[52:55], v[140:143], v[188:191], v[52:55]
	v_mfma_i32_16x16x64_i8 v[48:51], v[148:151], v[188:191], v[48:51]
	v_mfma_i32_16x16x64_i8 v[40:43], v[140:143], v[196:199], v[40:43]
	v_mfma_i32_16x16x64_i8 v[32:35], v[148:151], v[196:199], v[32:35]
	v_mfma_i32_16x16x64_i8 v[24:27], v[140:143], v[204:207], v[24:27]
	v_mfma_i32_16x16x64_i8 v[16:19], v[148:151], v[204:207], v[16:19]
	v_mfma_i32_16x16x64_i8 v[60:63], v[144:147], v[184:187], v[60:63]
	v_mfma_i32_16x16x64_i8 v[56:59], v[152:155], v[184:187], v[56:59]
	v_mfma_i32_16x16x64_i8 v[52:55], v[144:147], v[192:195], v[52:55]
	v_mfma_i32_16x16x64_i8 v[48:51], v[152:155], v[192:195], v[48:51]
	v_mfma_i32_16x16x64_i8 v[40:43], v[144:147], v[200:203], v[40:43]
	v_mfma_i32_16x16x64_i8 v[32:35], v[152:155], v[200:203], v[32:35]
	v_mfma_i32_16x16x64_i8 v[24:27], v[144:147], v[208:211], v[24:27]
	v_mfma_i32_16x16x64_i8 v[16:19], v[152:155], v[208:211], v[16:19]
	s_setprio 0
	s_setprio 1
	v_mfma_i32_16x16x64_i8 v[44:47], v[156:159], v[180:183], v[44:47]
	v_mfma_i32_16x16x64_i8 v[36:39], v[164:167], v[180:183], v[36:39]
	v_mfma_i32_16x16x64_i8 v[28:31], v[156:159], v[188:191], v[28:31]
	v_mfma_i32_16x16x64_i8 v[20:23], v[164:167], v[188:191], v[20:23]
	v_mfma_i32_16x16x64_i8 v[12:15], v[156:159], v[196:199], v[12:15]
	v_mfma_i32_16x16x64_i8 v[8:11], v[164:167], v[196:199], v[8:11]
	v_mfma_i32_16x16x64_i8 v[4:7], v[156:159], v[204:207], v[4:7]
	v_mfma_i32_16x16x64_i8 v[0:3], v[164:167], v[204:207], v[0:3]
	v_mfma_i32_16x16x64_i8 v[44:47], v[160:163], v[184:187], v[44:47]
	v_mfma_i32_16x16x64_i8 v[36:39], v[168:171], v[184:187], v[36:39]
	v_mfma_i32_16x16x64_i8 v[28:31], v[160:163], v[192:195], v[28:31]
	v_mfma_i32_16x16x64_i8 v[20:23], v[168:171], v[192:195], v[20:23]
	v_mfma_i32_16x16x64_i8 v[12:15], v[160:163], v[200:203], v[12:15]
	v_mfma_i32_16x16x64_i8 v[8:11], v[168:171], v[200:203], v[8:11]
	v_mfma_i32_16x16x64_i8 v[4:7], v[160:163], v[208:211], v[4:7]
	v_mfma_i32_16x16x64_i8 v[0:3], v[168:171], v[208:211], v[0:3]
	s_setprio 0
	s_barrier
	s_add_i32 s75, 0, 0x18000
	s_add_i32 s76, 0, 0x1c000
	v_add_u32_e32 v152, s75, v177
	v_add_u32_e32 v168, s76, v177
	ds_read_b128 v[140:143], v152
	ds_read_b128 v[144:147], v152 offset:1024
	ds_read_b128 v[148:151], v152 offset:2048
	ds_read_b128 v[152:155], v152 offset:3072
	ds_read_b128 v[156:159], v168
	ds_read_b128 v[160:163], v168 offset:1024
	ds_read_b128 v[164:167], v168 offset:2048
	ds_read_b128 v[168:171], v168 offset:3072
	s_add_u32 s40, s40, 0x80000
	s_addc_u32 s41, s41, 0
	s_mov_b32 m0, s47
	ds_read_b128 v[180:183], v178 offset:32768
	ds_read_b128 v[184:187], v178 offset:33792
	ds_read_b128 v[188:191], v178 offset:34816
	ds_read_b128 v[192:195], v178 offset:35840
	ds_read_b128 v[196:199], v178 offset:36864
	ds_read_b128 v[200:203], v178 offset:37888
	ds_read_b128 v[204:207], v178 offset:38912
	ds_read_b128 v[208:211], v178 offset:39936
	global_load_lds_dwordx4 v128, s[40:41]
	s_mov_b32 m0, s48
	s_nop 0
	global_load_lds_dwordx4 v132, s[40:41]
	s_waitcnt vmcnt(9)
	s_waitcnt lgkmcnt(0)
	s_barrier
	s_setprio 1
	s_waitcnt lgkmcnt(0)
	v_mfma_i32_16x16x64_i8 v[124:127], v[140:143], v[180:183], v[124:127]
	v_mfma_i32_16x16x64_i8 v[120:123], v[148:151], v[180:183], v[120:123]
	v_mfma_i32_16x16x64_i8 v[116:119], v[140:143], v[188:191], v[116:119]
	v_mfma_i32_16x16x64_i8 v[112:115], v[148:151], v[188:191], v[112:115]
	v_mfma_i32_16x16x64_i8 v[104:107], v[140:143], v[196:199], v[104:107]
	v_mfma_i32_16x16x64_i8 v[96:99], v[148:151], v[196:199], v[96:99]
	v_mfma_i32_16x16x64_i8 v[88:91], v[140:143], v[204:207], v[88:91]
	v_mfma_i32_16x16x64_i8 v[80:83], v[148:151], v[204:207], v[80:83]
	v_mfma_i32_16x16x64_i8 v[124:127], v[144:147], v[184:187], v[124:127]
	v_mfma_i32_16x16x64_i8 v[120:123], v[152:155], v[184:187], v[120:123]
	v_mfma_i32_16x16x64_i8 v[116:119], v[144:147], v[192:195], v[116:119]
	v_mfma_i32_16x16x64_i8 v[112:115], v[152:155], v[192:195], v[112:115]
	v_mfma_i32_16x16x64_i8 v[104:107], v[144:147], v[200:203], v[104:107]
	v_mfma_i32_16x16x64_i8 v[96:99], v[152:155], v[200:203], v[96:99]
	v_mfma_i32_16x16x64_i8 v[88:91], v[144:147], v[208:211], v[88:91]
	v_mfma_i32_16x16x64_i8 v[80:83], v[152:155], v[208:211], v[80:83]
	s_setprio 0
	s_setprio 1
	v_mfma_i32_16x16x64_i8 v[108:111], v[156:159], v[180:183], v[108:111]
	v_mfma_i32_16x16x64_i8 v[100:103], v[164:167], v[180:183], v[100:103]
	v_mfma_i32_16x16x64_i8 v[92:95], v[156:159], v[188:191], v[92:95]
	v_mfma_i32_16x16x64_i8 v[84:87], v[164:167], v[188:191], v[84:87]
	v_mfma_i32_16x16x64_i8 v[76:79], v[156:159], v[196:199], v[76:79]
	v_mfma_i32_16x16x64_i8 v[72:75], v[164:167], v[196:199], v[72:75]
	v_mfma_i32_16x16x64_i8 v[68:71], v[156:159], v[204:207], v[68:71]
	v_mfma_i32_16x16x64_i8 v[64:67], v[164:167], v[204:207], v[64:67]
	v_mfma_i32_16x16x64_i8 v[108:111], v[160:163], v[184:187], v[108:111]
	v_mfma_i32_16x16x64_i8 v[100:103], v[168:171], v[184:187], v[100:103]
	v_mfma_i32_16x16x64_i8 v[92:95], v[160:163], v[192:195], v[92:95]
	v_mfma_i32_16x16x64_i8 v[84:87], v[168:171], v[192:195], v[84:87]
	v_mfma_i32_16x16x64_i8 v[76:79], v[160:163], v[200:203], v[76:79]
	v_mfma_i32_16x16x64_i8 v[72:75], v[168:171], v[200:203], v[72:75]
	v_mfma_i32_16x16x64_i8 v[68:71], v[160:163], v[208:211], v[68:71]
	v_mfma_i32_16x16x64_i8 v[64:67], v[168:171], v[208:211], v[64:67]
	s_setprio 0
	s_barrier
	s_add_i32 s40, s75, s42
	v_lshl_add_u64 v[172:173], v[172:173], 0, s[20:21]
	s_mov_b32 m0, s40
	ds_read_b128 v[180:183], v178 offset:49152
	ds_read_b128 v[184:187], v178 offset:50176
	ds_read_b128 v[188:191], v178 offset:51200
	ds_read_b128 v[192:195], v178 offset:52224
	ds_read_b128 v[196:199], v178 offset:53248
	ds_read_b128 v[200:203], v178 offset:54272
	ds_read_b128 v[204:207], v178 offset:55296
	ds_read_b128 v[208:211], v178 offset:56320
	global_load_lds_dwordx4 v[172:173], off
	s_add_i32 m0, s40, 0x2000
	s_add_u32 s38, s38, 0x80080
	v_lshl_add_u64 v[172:173], v[212:213], 0, s[20:21]
	s_addc_u32 s39, s39, 0
	s_add_i32 s40, s76, s42
	global_load_lds_dwordx4 v[172:173], off
	s_mov_b32 m0, s40
	s_nop 0
	global_load_lds_dwordx4 v130, s[38:39]
	s_add_i32 m0, s40, 0x2000
	s_nop 0
	global_load_lds_dwordx4 v134, s[38:39]
	v_lshl_add_u64 v[172:173], v[214:215], 0, s[20:21]
	s_mov_b32 m0, s51
	s_nop 0
	global_load_lds_dwordx4 v[172:173], off
	v_lshl_add_u64 v[172:173], v[216:217], 0, s[20:21]
	s_mov_b32 m0, s52
	s_nop 0
	global_load_lds_dwordx4 v[172:173], off
	s_waitcnt vmcnt(8)
	s_waitcnt lgkmcnt(0)
	s_barrier
	s_setprio 1
	s_waitcnt lgkmcnt(0)
	v_mfma_i32_16x16x64_i8 v[60:63], v[140:143], v[180:183], v[60:63]
	v_mfma_i32_16x16x64_i8 v[56:59], v[148:151], v[180:183], v[56:59]
	v_mfma_i32_16x16x64_i8 v[52:55], v[140:143], v[188:191], v[52:55]
	v_fmaak_f32 v226, v226, v220, 0x4b400000
	v_mfma_i32_16x16x64_i8 v[48:51], v[148:151], v[188:191], v[48:51]
	v_mfma_i32_16x16x64_i8 v[40:43], v[140:143], v[196:199], v[40:43]
	v_mfma_i32_16x16x64_i8 v[32:35], v[148:151], v[196:199], v[32:35]
	v_fmaak_f32 v227, v227, v225, 0x4b400000
	v_mfma_i32_16x16x64_i8 v[24:27], v[140:143], v[204:207], v[24:27]
	v_mfma_i32_16x16x64_i8 v[16:19], v[148:151], v[204:207], v[16:19]
	v_mfma_i32_16x16x64_i8 v[60:63], v[144:147], v[184:187], v[60:63]
	v_fmaak_f32 v228, v228, v252, 0x4b400000
	v_mfma_i32_16x16x64_i8 v[56:59], v[152:155], v[184:187], v[56:59]
	v_mfma_i32_16x16x64_i8 v[52:55], v[144:147], v[192:195], v[52:55]
	v_mfma_i32_16x16x64_i8 v[48:51], v[152:155], v[192:195], v[48:51]
	v_fmaak_f32 v229, v229, v253, 0x4b400000
	v_mfma_i32_16x16x64_i8 v[40:43], v[144:147], v[200:203], v[40:43]
	v_mfma_i32_16x16x64_i8 v[32:35], v[152:155], v[200:203], v[32:35]
	v_mfma_i32_16x16x64_i8 v[24:27], v[144:147], v[208:211], v[24:27]
	v_alignbit_b32 v239, v226, v239, 8
	v_mfma_i32_16x16x64_i8 v[16:19], v[152:155], v[208:211], v[16:19]
	s_setprio 0
	s_setprio 1
	v_mfma_i32_16x16x64_i8 v[44:47], v[156:159], v[180:183], v[44:47]
	v_mfma_i32_16x16x64_i8 v[36:39], v[164:167], v[180:183], v[36:39]
	v_alignbit_b32 v243, v227, v243, 8
	v_mfma_i32_16x16x64_i8 v[28:31], v[156:159], v[188:191], v[28:31]
	v_mfma_i32_16x16x64_i8 v[20:23], v[164:167], v[188:191], v[20:23]
	v_mfma_i32_16x16x64_i8 v[12:15], v[156:159], v[196:199], v[12:15]
	v_alignbit_b32 v247, v228, v247, 8
	v_mfma_i32_16x16x64_i8 v[8:11], v[164:167], v[196:199], v[8:11]
	v_mfma_i32_16x16x64_i8 v[4:7], v[156:159], v[204:207], v[4:7]
	v_mfma_i32_16x16x64_i8 v[0:3], v[164:167], v[204:207], v[0:3]
	v_alignbit_b32 v251, v229, v251, 8
	v_mfma_i32_16x16x64_i8 v[44:47], v[160:163], v[184:187], v[44:47]
	v_mfma_i32_16x16x64_i8 v[36:39], v[168:171], v[184:187], v[36:39]
	v_mfma_i32_16x16x64_i8 v[28:31], v[160:163], v[192:195], v[28:31]
	v_add_u32_e32 v223, 0x4000, v223
	v_mfma_i32_16x16x64_i8 v[20:23], v[168:171], v[192:195], v[20:23]
	v_mfma_i32_16x16x64_i8 v[12:15], v[160:163], v[200:203], v[12:15]
	v_mfma_i32_16x16x64_i8 v[8:11], v[168:171], v[200:203], v[8:11]
	v_mfma_i32_16x16x64_i8 v[4:7], v[160:163], v[208:211], v[4:7]
	v_mfma_i32_16x16x64_i8 v[0:3], v[168:171], v[208:211], v[0:3]
	s_setprio 0
	s_barrier
	s_and_b32 s77, s84, 3
	s_cbranch_scc0 .Lq_mv_L

.Lq_body_ST:
	s_add_i32 s74, s38, 2
	s_add_u32 s39, s36, 0xfff80080
	s_addc_u32 s40, s37, -1
	s_cmp_eq_u32 s71, s38
	s_cselect_b32 s41, s67, s40
	s_cselect_b32 s40, s68, s39
	v_add_u32_e32 v152, s55, v177
	v_add_u32_e32 v168, s60, v177
	ds_read_b128 v[140:143], v152
	ds_read_b128 v[144:147], v152 offset:1024
	ds_read_b128 v[148:151], v152 offset:2048
	ds_read_b128 v[152:155], v152 offset:3072
	ds_read_b128 v[156:159], v168
	ds_read_b128 v[160:163], v168 offset:1024
	ds_read_b128 v[164:167], v168 offset:2048
	ds_read_b128 v[168:171], v168 offset:3072
	s_cselect_b32 s38, s70, s72
	s_cselect_b32 s39, s69, s73
	s_add_i32 m0, s45, 0xc000
	ds_read_b128 v[180:183], v178
	ds_read_b128 v[184:187], v178 offset:1024
	ds_read_b128 v[188:191], v178 offset:2048
	ds_read_b128 v[192:195], v178 offset:3072
	ds_read_b128 v[196:199], v178 offset:4096
	ds_read_b128 v[200:203], v178 offset:5120
	ds_read_b128 v[204:207], v178 offset:6144
	ds_read_b128 v[208:211], v178 offset:7168
	global_load_lds_dwordx4 v136, s[36:37]
	s_add_i32 m0, s45, 0xe000
	s_nop 0
	global_load_lds_dwordx4 v138, s[36:37]
	global_store_dwordx4 v224, v[236:239], s[98:99]
	s_add_u32 s98, s98, 0x2b00
	s_addc_u32 s99, s99, 0
	global_store_dwordx4 v224, v[240:243], s[98:99]
	s_add_u32 s98, s98, 0x2b00
	s_addc_u32 s99, s99, 0
	global_store_dwordx4 v224, v[244:247], s[98:99]
	s_add_u32 s98, s98, 0x2b00
	s_addc_u32 s99, s99, 0
	global_store_dwordx4 v224, v[248:251], s[98:99]
	v_subrev_u32_e32 v223, 0x40000, v223
	s_cmp_lt_u32 s84, s87
	s_cbranch_scc0 .Lq_st_last
	s_cmp_lt_u32 s84, s89
	s_cbranch_scc0 .Lq_st_full
	s_sub_u32 s98, s98, 0x8080
	s_subb_u32 s99, s99, 0
	s_add_u32 s100, s100, 0x200000
	s_addc_u32 s101, s101, 0

.Lq_st_j:
	s_waitcnt vmcnt(13)
	s_waitcnt lgkmcnt(0)
	s_barrier
	s_setprio 1
	s_waitcnt lgkmcnt(0)
	v_mfma_i32_16x16x64_i8 v[124:127], v[140:143], v[180:183], v[124:127]
	v_mfma_i32_16x16x64_i8 v[120:123], v[148:151], v[180:183], v[120:123]
	v_mfma_i32_16x16x64_i8 v[116:119], v[140:143], v[188:191], v[116:119]
	v_mfma_i32_16x16x64_i8 v[112:115], v[148:151], v[188:191], v[112:115]
	v_mfma_i32_16x16x64_i8 v[104:107], v[140:143], v[196:199], v[104:107]
	v_mfma_i32_16x16x64_i8 v[96:99], v[148:151], v[196:199], v[96:99]
	v_mfma_i32_16x16x64_i8 v[88:91], v[140:143], v[204:207], v[88:91]
	v_mfma_i32_16x16x64_i8 v[80:83], v[148:151], v[204:207], v[80:83]
	v_mfma_i32_16x16x64_i8 v[124:127], v[144:147], v[184:187], v[124:127]
	v_mfma_i32_16x16x64_i8 v[120:123], v[152:155], v[184:187], v[120:123]
	v_mfma_i32_16x16x64_i8 v[116:119], v[144:147], v[192:195], v[116:119]
	v_mfma_i32_16x16x64_i8 v[112:115], v[152:155], v[192:195], v[112:115]
	v_mfma_i32_16x16x64_i8 v[104:107], v[144:147], v[200:203], v[104:107]
	v_mfma_i32_16x16x64_i8 v[96:99], v[152:155], v[200:203], v[96:99]
	v_mfma_i32_16x16x64_i8 v[88:91], v[144:147], v[208:211], v[88:91]
	v_mfma_i32_16x16x64_i8 v[80:83], v[152:155], v[208:211], v[80:83]
	s_setprio 0
	s_setprio 1
	v_mfma_i32_16x16x64_i8 v[108:111], v[156:159], v[180:183], v[108:111]
	v_mfma_i32_16x16x64_i8 v[100:103], v[164:167], v[180:183], v[100:103]
	v_mfma_i32_16x16x64_i8 v[92:95], v[156:159], v[188:191], v[92:95]
	v_mfma_i32_16x16x64_i8 v[84:87], v[164:167], v[188:191], v[84:87]
	v_mfma_i32_16x16x64_i8 v[76:79], v[156:159], v[196:199], v[76:79]
	v_mfma_i32_16x16x64_i8 v[72:75], v[164:167], v[196:199], v[72:75]
	v_mfma_i32_16x16x64_i8 v[68:71], v[156:159], v[204:207], v[68:71]
	v_mfma_i32_16x16x64_i8 v[64:67], v[164:167], v[204:207], v[64:67]
	v_mfma_i32_16x16x64_i8 v[108:111], v[160:163], v[184:187], v[108:111]
	v_mfma_i32_16x16x64_i8 v[100:103], v[168:171], v[184:187], v[100:103]
	v_mfma_i32_16x16x64_i8 v[92:95], v[160:163], v[192:195], v[92:95]
	v_mfma_i32_16x16x64_i8 v[84:87], v[168:171], v[192:195], v[84:87]
	v_mfma_i32_16x16x64_i8 v[76:79], v[160:163], v[200:203], v[76:79]
	v_mfma_i32_16x16x64_i8 v[72:75], v[168:171], v[200:203], v[72:75]
	v_mfma_i32_16x16x64_i8 v[68:71], v[160:163], v[208:211], v[68:71]
	v_mfma_i32_16x16x64_i8 v[64:67], v[168:171], v[208:211], v[64:67]
	s_setprio 0
	s_barrier
	s_add_i32 s75, s55, s42
	v_lshl_add_u64 v[172:173], s[38:39], 0, v[130:131]
	s_mov_b32 m0, s75
	ds_read_b128 v[180:183], v178 offset:16384
	ds_read_b128 v[184:187], v178 offset:17408
	ds_read_b128 v[188:191], v178 offset:18432
	ds_read_b128 v[192:195], v178 offset:19456
	ds_read_b128 v[196:199], v178 offset:20480
	ds_read_b128 v[200:203], v178 offset:21504
	ds_read_b128 v[204:207], v178 offset:22528
	ds_read_b128 v[208:211], v178 offset:23552
	global_load_lds_dwordx4 v130, s[38:39]
	s_add_i32 m0, s75, 0x2000
	s_add_u32 s76, s38, 0x80000
	v_lshl_add_u64 v[212:213], s[38:39], 0, v[134:135]
	s_addc_u32 s77, s39, 0
	s_add_i32 s75, s60, s42
	global_load_lds_dwordx4 v134, s[38:39]
	s_mov_b32 m0, s75
	v_lshl_add_u64 v[216:217], s[40:41], 0, v[132:133]
	global_load_lds_dwordx4 v130, s[76:77]
	s_add_i32 m0, s75, 0x2000
	s_nop 0
	global_load_lds_dwordx4 v134, s[76:77]
	v_lshl_add_u64 v[214:215], s[40:41], 0, v[128:129]
	s_mov_b32 m0, s45
	s_nop 0
	global_load_lds_dwordx4 v128, s[40:41]
	s_mov_b32 m0, s46
	s_nop 0
	global_load_lds_dwordx4 v132, s[40:41]
	s_waitcnt vmcnt(13)
	s_waitcnt lgkmcnt(0)
	s_barrier
	s_setprio 1
	s_waitcnt lgkmcnt(0)
	v_mfma_i32_16x16x64_i8 v[60:63], v[140:143], v[180:183], v[60:63]
	v_mfma_i32_16x16x64_i8 v[56:59], v[148:151], v[180:183], v[56:59]
	v_mfma_i32_16x16x64_i8 v[52:55], v[140:143], v[188:191], v[52:55]
	v_mfma_i32_16x16x64_i8 v[48:51], v[148:151], v[188:191], v[48:51]
	v_mfma_i32_16x16x64_i8 v[40:43], v[140:143], v[196:199], v[40:43]
	v_mfma_i32_16x16x64_i8 v[32:35], v[148:151], v[196:199], v[32:35]
	v_mfma_i32_16x16x64_i8 v[24:27], v[140:143], v[204:207], v[24:27]
	v_mfma_i32_16x16x64_i8 v[16:19], v[148:151], v[204:207], v[16:19]
	v_mfma_i32_16x16x64_i8 v[60:63], v[144:147], v[184:187], v[60:63]
	v_mfma_i32_16x16x64_i8 v[56:59], v[152:155], v[184:187], v[56:59]
	v_mfma_i32_16x16x64_i8 v[52:55], v[144:147], v[192:195], v[52:55]
	v_mfma_i32_16x16x64_i8 v[48:51], v[152:155], v[192:195], v[48:51]
	v_mfma_i32_16x16x64_i8 v[40:43], v[144:147], v[200:203], v[40:43]
	v_mfma_i32_16x16x64_i8 v[32:35], v[152:155], v[200:203], v[32:35]
	v_mfma_i32_16x16x64_i8 v[24:27], v[144:147], v[208:211], v[24:27]
	v_mfma_i32_16x16x64_i8 v[16:19], v[152:155], v[208:211], v[16:19]
	s_setprio 0
	s_setprio 1
	v_mfma_i32_16x16x64_i8 v[44:47], v[156:159], v[180:183], v[44:47]
	v_mfma_i32_16x16x64_i8 v[36:39], v[164:167], v[180:183], v[36:39]
	v_mfma_i32_16x16x64_i8 v[28:31], v[156:159], v[188:191], v[28:31]
	v_mfma_i32_16x16x64_i8 v[20:23], v[164:167], v[188:191], v[20:23]
	v_mfma_i32_16x16x64_i8 v[12:15], v[156:159], v[196:199], v[12:15]
	v_mfma_i32_16x16x64_i8 v[8:11], v[164:167], v[196:199], v[8:11]
	v_mfma_i32_16x16x64_i8 v[4:7], v[156:159], v[204:207], v[4:7]
	v_mfma_i32_16x16x64_i8 v[0:3], v[164:167], v[204:207], v[0:3]
	v_mfma_i32_16x16x64_i8 v[44:47], v[160:163], v[184:187], v[44:47]
	v_mfma_i32_16x16x64_i8 v[36:39], v[168:171], v[184:187], v[36:39]
	v_mfma_i32_16x16x64_i8 v[28:31], v[160:163], v[192:195], v[28:31]
	v_mfma_i32_16x16x64_i8 v[20:23], v[168:171], v[192:195], v[20:23]
	v_mfma_i32_16x16x64_i8 v[12:15], v[160:163], v[200:203], v[12:15]
	v_mfma_i32_16x16x64_i8 v[8:11], v[168:171], v[200:203], v[8:11]
	v_mfma_i32_16x16x64_i8 v[4:7], v[160:163], v[208:211], v[4:7]
	v_mfma_i32_16x16x64_i8 v[0:3], v[168:171], v[208:211], v[0:3]
	s_setprio 0
	s_barrier
	s_add_i32 s75, 0, 0x18000
	s_add_i32 s76, 0, 0x1c000
	v_add_u32_e32 v152, s75, v177
	v_add_u32_e32 v168, s76, v177
	ds_read_b128 v[140:143], v152
	ds_read_b128 v[144:147], v152 offset:1024
	ds_read_b128 v[148:151], v152 offset:2048
	ds_read_b128 v[152:155], v152 offset:3072
	ds_read_b128 v[156:159], v168
	ds_read_b128 v[160:163], v168 offset:1024
	ds_read_b128 v[164:167], v168 offset:2048
	ds_read_b128 v[168:171], v168 offset:3072
	s_add_u32 s40, s40, 0x80000
	s_addc_u32 s41, s41, 0
	s_mov_b32 m0, s47
	ds_read_b128 v[180:183], v178 offset:32768
	ds_read_b128 v[184:187], v178 offset:33792
	ds_read_b128 v[188:191], v178 offset:34816
	ds_read_b128 v[192:195], v178 offset:35840
	ds_read_b128 v[196:199], v178 offset:36864
	ds_read_b128 v[200:203], v178 offset:37888
	ds_read_b128 v[204:207], v178 offset:38912
	ds_read_b128 v[208:211], v178 offset:39936
	global_load_lds_dwordx4 v128, s[40:41]
	s_mov_b32 m0, s48
	s_nop 0
	global_load_lds_dwordx4 v132, s[40:41]
	s_waitcnt vmcnt(13)
	s_waitcnt lgkmcnt(0)
	s_barrier
	s_setprio 1
	s_waitcnt lgkmcnt(0)
	v_mfma_i32_16x16x64_i8 v[124:127], v[140:143], v[180:183], v[124:127]
	v_mfma_i32_16x16x64_i8 v[120:123], v[148:151], v[180:183], v[120:123]
	v_mfma_i32_16x16x64_i8 v[116:119], v[140:143], v[188:191], v[116:119]
	v_mfma_i32_16x16x64_i8 v[112:115], v[148:151], v[188:191], v[112:115]
	v_mfma_i32_16x16x64_i8 v[104:107], v[140:143], v[196:199], v[104:107]
	v_mfma_i32_16x16x64_i8 v[96:99], v[148:151], v[196:199], v[96:99]
	v_mfma_i32_16x16x64_i8 v[88:91], v[140:143], v[204:207], v[88:91]
	v_mfma_i32_16x16x64_i8 v[80:83], v[148:151], v[204:207], v[80:83]
	v_mfma_i32_16x16x64_i8 v[124:127], v[144:147], v[184:187], v[124:127]
	v_mfma_i32_16x16x64_i8 v[120:123], v[152:155], v[184:187], v[120:123]
	v_mfma_i32_16x16x64_i8 v[116:119], v[144:147], v[192:195], v[116:119]
	v_mfma_i32_16x16x64_i8 v[112:115], v[152:155], v[192:195], v[112:115]
	v_mfma_i32_16x16x64_i8 v[104:107], v[144:147], v[200:203], v[104:107]
	v_mfma_i32_16x16x64_i8 v[96:99], v[152:155], v[200:203], v[96:99]
	v_mfma_i32_16x16x64_i8 v[88:91], v[144:147], v[208:211], v[88:91]
	v_mfma_i32_16x16x64_i8 v[80:83], v[152:155], v[208:211], v[80:83]
	s_setprio 0
	s_setprio 1
	v_mfma_i32_16x16x64_i8 v[108:111], v[156:159], v[180:183], v[108:111]
	v_mfma_i32_16x16x64_i8 v[100:103], v[164:167], v[180:183], v[100:103]
	v_mfma_i32_16x16x64_i8 v[92:95], v[156:159], v[188:191], v[92:95]
	v_mfma_i32_16x16x64_i8 v[84:87], v[164:167], v[188:191], v[84:87]
	v_mfma_i32_16x16x64_i8 v[76:79], v[156:159], v[196:199], v[76:79]
	v_mfma_i32_16x16x64_i8 v[72:75], v[164:167], v[196:199], v[72:75]
	v_mfma_i32_16x16x64_i8 v[68:71], v[156:159], v[204:207], v[68:71]
	v_mfma_i32_16x16x64_i8 v[64:67], v[164:167], v[204:207], v[64:67]
	v_mfma_i32_16x16x64_i8 v[108:111], v[160:163], v[184:187], v[108:111]
	v_mfma_i32_16x16x64_i8 v[100:103], v[168:171], v[184:187], v[100:103]
	v_mfma_i32_16x16x64_i8 v[92:95], v[160:163], v[192:195], v[92:95]
	v_mfma_i32_16x16x64_i8 v[84:87], v[168:171], v[192:195], v[84:87]
	v_mfma_i32_16x16x64_i8 v[76:79], v[160:163], v[200:203], v[76:79]
	v_mfma_i32_16x16x64_i8 v[72:75], v[168:171], v[200:203], v[72:75]
	v_mfma_i32_16x16x64_i8 v[68:71], v[160:163], v[208:211], v[68:71]
	v_mfma_i32_16x16x64_i8 v[64:67], v[168:171], v[208:211], v[64:67]
	s_setprio 0
	s_barrier
	s_add_i32 s40, s75, s42
	v_lshl_add_u64 v[172:173], v[172:173], 0, s[20:21]
	s_mov_b32 m0, s40
	ds_read_b128 v[180:183], v178 offset:49152
	ds_read_b128 v[184:187], v178 offset:50176
	ds_read_b128 v[188:191], v178 offset:51200
	ds_read_b128 v[192:195], v178 offset:52224
	ds_read_b128 v[196:199], v178 offset:53248
	ds_read_b128 v[200:203], v178 offset:54272
	ds_read_b128 v[204:207], v178 offset:55296
	ds_read_b128 v[208:211], v178 offset:56320
	global_load_lds_dwordx4 v[172:173], off
	s_add_i32 m0, s40, 0x2000
	s_add_u32 s38, s38, 0x80080
	v_lshl_add_u64 v[172:173], v[212:213], 0, s[20:21]
	s_addc_u32 s39, s39, 0
	s_add_i32 s40, s76, s42
	global_load_lds_dwordx4 v[172:173], off
	s_mov_b32 m0, s40
	s_nop 0
	global_load_lds_dwordx4 v130, s[38:39]
	s_add_i32 m0, s40, 0x2000
	s_nop 0
	global_load_lds_dwordx4 v134, s[38:39]
	v_lshl_add_u64 v[172:173], v[214:215], 0, s[20:21]
	s_mov_b32 m0, s51
	s_nop 0
	global_load_lds_dwordx4 v[172:173], off
	v_lshl_add_u64 v[172:173], v[216:217], 0, s[20:21]
	s_mov_b32 m0, s52
	s_nop 0
	global_load_lds_dwordx4 v[172:173], off
	s_waitcnt vmcnt(8)
	s_waitcnt lgkmcnt(0)
	s_barrier
	s_setprio 1
	s_waitcnt lgkmcnt(0)
	v_mfma_i32_16x16x64_i8 v[60:63], v[140:143], v[180:183], v[60:63]
	v_mfma_i32_16x16x64_i8 v[56:59], v[148:151], v[180:183], v[56:59]
	v_mfma_i32_16x16x64_i8 v[52:55], v[140:143], v[188:191], v[52:55]
	v_fmaak_f32 v226, v226, v220, 0x4b400000
	v_mfma_i32_16x16x64_i8 v[48:51], v[148:151], v[188:191], v[48:51]
	v_mfma_i32_16x16x64_i8 v[40:43], v[140:143], v[196:199], v[40:43]
	v_mfma_i32_16x16x64_i8 v[32:35], v[148:151], v[196:199], v[32:35]
	v_fmaak_f32 v227, v227, v225, 0x4b400000
	v_mfma_i32_16x16x64_i8 v[24:27], v[140:143], v[204:207], v[24:27]
	v_mfma_i32_16x16x64_i8 v[16:19], v[148:151], v[204:207], v[16:19]
	v_mfma_i32_16x16x64_i8 v[60:63], v[144:147], v[184:187], v[60:63]
	v_fmaak_f32 v228, v228, v252, 0x4b400000
	v_mfma_i32_16x16x64_i8 v[56:59], v[152:155], v[184:187], v[56:59]
	v_mfma_i32_16x16x64_i8 v[52:55], v[144:147], v[192:195], v[52:55]
	v_mfma_i32_16x16x64_i8 v[48:51], v[152:155], v[192:195], v[48:51]
	v_fmaak_f32 v229, v229, v253, 0x4b400000
	v_mfma_i32_16x16x64_i8 v[40:43], v[144:147], v[200:203], v[40:43]
	v_mfma_i32_16x16x64_i8 v[32:35], v[152:155], v[200:203], v[32:35]
	v_mfma_i32_16x16x64_i8 v[24:27], v[144:147], v[208:211], v[24:27]
	v_alignbit_b32 v239, v226, v239, 8
	v_mfma_i32_16x16x64_i8 v[16:19], v[152:155], v[208:211], v[16:19]
	s_setprio 0
	s_setprio 1
	v_mfma_i32_16x16x64_i8 v[44:47], v[156:159], v[180:183], v[44:47]
	v_mfma_i32_16x16x64_i8 v[36:39], v[164:167], v[180:183], v[36:39]
	v_alignbit_b32 v243, v227, v243, 8
	v_mfma_i32_16x16x64_i8 v[28:31], v[156:159], v[188:191], v[28:31]
	v_mfma_i32_16x16x64_i8 v[20:23], v[164:167], v[188:191], v[20:23]
	v_mfma_i32_16x16x64_i8 v[12:15], v[156:159], v[196:199], v[12:15]
	v_alignbit_b32 v247, v228, v247, 8
	v_mfma_i32_16x16x64_i8 v[8:11], v[164:167], v[196:199], v[8:11]
	v_mfma_i32_16x16x64_i8 v[4:7], v[156:159], v[204:207], v[4:7]
	v_mfma_i32_16x16x64_i8 v[0:3], v[164:167], v[204:207], v[0:3]
	v_alignbit_b32 v251, v229, v251, 8
	v_mfma_i32_16x16x64_i8 v[44:47], v[160:163], v[184:187], v[44:47]
	v_mfma_i32_16x16x64_i8 v[36:39], v[168:171], v[184:187], v[36:39]
	v_mfma_i32_16x16x64_i8 v[28:31], v[160:163], v[192:195], v[28:31]
	v_add_u32_e32 v223, 0x4000, v223
	v_mfma_i32_16x16x64_i8 v[20:23], v[168:171], v[192:195], v[20:23]
	v_mfma_i32_16x16x64_i8 v[12:15], v[160:163], v[200:203], v[12:15]
	v_mfma_i32_16x16x64_i8 v[8:11], v[168:171], v[200:203], v[8:11]
	v_mfma_i32_16x16x64_i8 v[4:7], v[160:163], v[208:211], v[4:7]
	v_mfma_i32_16x16x64_i8 v[0:3], v[168:171], v[208:211], v[0:3]
	s_setprio 0
	s_barrier
	s_cmp_eq_u32 s32, 0
	s_cbranch_scc1 .Lq_mvx_ST
	s_and_b32 s77, s84, 3
	s_cbranch_scc0 .Lq_mv_ST

.LBB0_1474:
	s_add_i32 s75, s48, 2
	s_add_u32 s46, s44, 0x100
	s_addc_u32 s47, s45, 0
	s_cmp_eq_u32 s72, s48
	s_cselect_b32 s51, s41, s47
	s_cselect_b32 s50, s40, s46
	v_add_u32_e32 v152, s66, v184
	v_add_u32_e32 v168, s67, v184
	ds_read_b128 v[140:143], v152
	ds_read_b128 v[144:147], v152 offset:1024
	ds_read_b128 v[148:151], v152 offset:2048
	ds_read_b128 v[152:155], v152 offset:3072
	ds_read_b128 v[156:159], v168
	ds_read_b128 v[160:163], v168 offset:1024
	ds_read_b128 v[164:167], v168 offset:2048
	ds_read_b128 v[168:171], v168 offset:3072
	s_cselect_b32 s48, s42, s73
	s_cselect_b32 s49, s43, s74
	s_add_i32 m0, s54, 0xc000
	ds_read_b128 v[172:175], v186
	ds_read_b128 v[176:179], v186 offset:1024
	ds_read_b128 v[188:191], v186 offset:2048
	ds_read_b128 v[192:195], v186 offset:3072
	ds_read_b128 v[196:199], v186 offset:4096
	ds_read_b128 v[200:203], v186 offset:5120
	ds_read_b128 v[204:207], v186 offset:6144
	ds_read_b128 v[208:211], v186 offset:7168
	global_load_lds_dwordx4 v136, s[44:45]
	s_add_i32 m0, s54, 0xe000
	s_nop 0
	global_load_lds_dwordx4 v138, s[44:45]
	s_waitcnt vmcnt(8)
	s_waitcnt lgkmcnt(0)
	s_barrier
	s_setprio 1
	s_waitcnt lgkmcnt(0)
	v_mfma_i32_16x16x64_i8 v[124:127], v[140:143], v[172:175], v[124:127]
	v_mfma_i32_16x16x64_i8 v[120:123], v[148:151], v[172:175], v[120:123]
	v_mfma_i32_16x16x64_i8 v[116:119], v[140:143], v[188:191], v[116:119]
	v_mfma_i32_16x16x64_i8 v[112:115], v[148:151], v[188:191], v[112:115]
	v_mfma_i32_16x16x64_i8 v[104:107], v[140:143], v[196:199], v[104:107]
	v_mfma_i32_16x16x64_i8 v[96:99], v[148:151], v[196:199], v[96:99]
	v_mfma_i32_16x16x64_i8 v[88:91], v[140:143], v[204:207], v[88:91]
	v_mfma_i32_16x16x64_i8 v[80:83], v[148:151], v[204:207], v[80:83]
	v_mfma_i32_16x16x64_i8 v[124:127], v[144:147], v[176:179], v[124:127]
	v_mfma_i32_16x16x64_i8 v[120:123], v[152:155], v[176:179], v[120:123]
	v_mfma_i32_16x16x64_i8 v[116:119], v[144:147], v[192:195], v[116:119]
	v_mfma_i32_16x16x64_i8 v[112:115], v[152:155], v[192:195], v[112:115]
	v_mfma_i32_16x16x64_i8 v[104:107], v[144:147], v[200:203], v[104:107]
	v_mfma_i32_16x16x64_i8 v[96:99], v[152:155], v[200:203], v[96:99]
	v_mfma_i32_16x16x64_i8 v[88:91], v[144:147], v[208:211], v[88:91]
	v_mfma_i32_16x16x64_i8 v[80:83], v[152:155], v[208:211], v[80:83]
	s_setprio 0
	s_setprio 1
	v_mfma_i32_16x16x64_i8 v[108:111], v[156:159], v[172:175], v[108:111]
	v_mfma_i32_16x16x64_i8 v[100:103], v[164:167], v[172:175], v[100:103]
	v_mfma_i32_16x16x64_i8 v[92:95], v[156:159], v[188:191], v[92:95]
	v_mfma_i32_16x16x64_i8 v[84:87], v[164:167], v[188:191], v[84:87]
	v_mfma_i32_16x16x64_i8 v[76:79], v[156:159], v[196:199], v[76:79]
	v_mfma_i32_16x16x64_i8 v[72:75], v[164:167], v[196:199], v[72:75]
	v_mfma_i32_16x16x64_i8 v[68:71], v[156:159], v[204:207], v[68:71]
	v_mfma_i32_16x16x64_i8 v[64:67], v[164:167], v[204:207], v[64:67]
	v_mfma_i32_16x16x64_i8 v[108:111], v[160:163], v[176:179], v[108:111]
	v_mfma_i32_16x16x64_i8 v[100:103], v[168:171], v[176:179], v[100:103]
	v_mfma_i32_16x16x64_i8 v[92:95], v[160:163], v[192:195], v[92:95]
	v_mfma_i32_16x16x64_i8 v[84:87], v[168:171], v[192:195], v[84:87]
	v_mfma_i32_16x16x64_i8 v[76:79], v[160:163], v[200:203], v[76:79]
	v_mfma_i32_16x16x64_i8 v[72:75], v[168:171], v[200:203], v[72:75]
	v_mfma_i32_16x16x64_i8 v[68:71], v[160:163], v[208:211], v[68:71]
	v_mfma_i32_16x16x64_i8 v[64:67], v[168:171], v[208:211], v[64:67]
	s_setprio 0
	s_barrier
	s_add_i32 s44, s66, s53
	s_mov_b32 m0, s44
	ds_read_b128 v[172:175], v186 offset:16384
	ds_read_b128 v[176:179], v186 offset:17408
	ds_read_b128 v[188:191], v186 offset:18432
	ds_read_b128 v[192:195], v186 offset:19456
	ds_read_b128 v[196:199], v186 offset:20480
	ds_read_b128 v[200:203], v186 offset:21504
	ds_read_b128 v[204:207], v186 offset:22528
	ds_read_b128 v[208:211], v186 offset:23552
	global_load_lds_dwordx4 v130, s[48:49]
	s_add_i32 m0, s44, 0x2000
	s_add_u32 s44, s48, 0x158000
	s_addc_u32 s45, s49, 0
	s_add_i32 s76, s67, s53
	global_load_lds_dwordx4 v134, s[48:49]
	s_mov_b32 m0, s76
	s_nop 0
	global_load_lds_dwordx4 v130, s[44:45]
	s_add_i32 m0, s76, 0x2000
	s_nop 0
	global_load_lds_dwordx4 v134, s[44:45]
	s_mov_b32 m0, s54
	s_nop 0
	global_load_lds_dwordx4 v128, s[50:51]
	s_mov_b32 m0, s55
	s_nop 0
	global_load_lds_dwordx4 v132, s[50:51]
	s_waitcnt vmcnt(8)
	s_waitcnt lgkmcnt(0)
	s_barrier
	s_setprio 1
	s_waitcnt lgkmcnt(0)
	v_mfma_i32_16x16x64_i8 v[60:63], v[140:143], v[172:175], v[60:63]
	v_mfma_i32_16x16x64_i8 v[56:59], v[148:151], v[172:175], v[56:59]
	v_mfma_i32_16x16x64_i8 v[52:55], v[140:143], v[188:191], v[52:55]
	v_mfma_i32_16x16x64_i8 v[48:51], v[148:151], v[188:191], v[48:51]
	v_mfma_i32_16x16x64_i8 v[40:43], v[140:143], v[196:199], v[40:43]
	v_mfma_i32_16x16x64_i8 v[32:35], v[148:151], v[196:199], v[32:35]
	v_mfma_i32_16x16x64_i8 v[24:27], v[140:143], v[204:207], v[24:27]
	v_mfma_i32_16x16x64_i8 v[16:19], v[148:151], v[204:207], v[16:19]
	v_mfma_i32_16x16x64_i8 v[60:63], v[144:147], v[176:179], v[60:63]
	v_mfma_i32_16x16x64_i8 v[56:59], v[152:155], v[176:179], v[56:59]
	v_mfma_i32_16x16x64_i8 v[52:55], v[144:147], v[192:195], v[52:55]
	v_mfma_i32_16x16x64_i8 v[48:51], v[152:155], v[192:195], v[48:51]
	v_mfma_i32_16x16x64_i8 v[40:43], v[144:147], v[200:203], v[40:43]
	v_mfma_i32_16x16x64_i8 v[32:35], v[152:155], v[200:203], v[32:35]
	v_mfma_i32_16x16x64_i8 v[24:27], v[144:147], v[208:211], v[24:27]
	v_mfma_i32_16x16x64_i8 v[16:19], v[152:155], v[208:211], v[16:19]
	s_setprio 0
	s_setprio 1
	v_mfma_i32_16x16x64_i8 v[44:47], v[156:159], v[172:175], v[44:47]
	v_mfma_i32_16x16x64_i8 v[36:39], v[164:167], v[172:175], v[36:39]
	v_mfma_i32_16x16x64_i8 v[28:31], v[156:159], v[188:191], v[28:31]
	v_mfma_i32_16x16x64_i8 v[20:23], v[164:167], v[188:191], v[20:23]
	v_mfma_i32_16x16x64_i8 v[12:15], v[156:159], v[196:199], v[12:15]
	v_mfma_i32_16x16x64_i8 v[8:11], v[164:167], v[196:199], v[8:11]
	v_mfma_i32_16x16x64_i8 v[4:7], v[156:159], v[204:207], v[4:7]
	v_mfma_i32_16x16x64_i8 v[0:3], v[164:167], v[204:207], v[0:3]
	v_mfma_i32_16x16x64_i8 v[44:47], v[160:163], v[176:179], v[44:47]
	v_mfma_i32_16x16x64_i8 v[36:39], v[168:171], v[176:179], v[36:39]
	v_mfma_i32_16x16x64_i8 v[28:31], v[160:163], v[192:195], v[28:31]
	v_mfma_i32_16x16x64_i8 v[20:23], v[168:171], v[192:195], v[20:23]
	v_mfma_i32_16x16x64_i8 v[12:15], v[160:163], v[200:203], v[12:15]
	v_mfma_i32_16x16x64_i8 v[8:11], v[168:171], v[200:203], v[8:11]
	v_mfma_i32_16x16x64_i8 v[4:7], v[160:163], v[208:211], v[4:7]
	v_mfma_i32_16x16x64_i8 v[0:3], v[168:171], v[208:211], v[0:3]
	s_setprio 0
	s_barrier
	s_add_i32 s76, 0, 0x18000
	s_add_i32 s77, 0, 0x1c000
	v_add_u32_e32 v152, s76, v184
	v_add_u32_e32 v168, s77, v184
	ds_read_b128 v[140:143], v152
	ds_read_b128 v[144:147], v152 offset:1024
	ds_read_b128 v[148:151], v152 offset:2048
	ds_read_b128 v[152:155], v152 offset:3072
	ds_read_b128 v[156:159], v168
	ds_read_b128 v[160:163], v168 offset:1024
	ds_read_b128 v[164:167], v168 offset:2048
	ds_read_b128 v[168:171], v168 offset:3072
	s_add_u32 s44, s50, 0x158000
	s_addc_u32 s45, s51, 0
	s_mov_b32 m0, s60
	ds_read_b128 v[172:175], v186 offset:32768
	ds_read_b128 v[176:179], v186 offset:33792
	ds_read_b128 v[188:191], v186 offset:34816
	ds_read_b128 v[192:195], v186 offset:35840
	ds_read_b128 v[196:199], v186 offset:36864
	ds_read_b128 v[200:203], v186 offset:37888
	ds_read_b128 v[204:207], v186 offset:38912
	ds_read_b128 v[208:211], v186 offset:39936
	global_load_lds_dwordx4 v128, s[44:45]
	s_mov_b32 m0, s61
	s_nop 0
	global_load_lds_dwordx4 v132, s[44:45]
	s_waitcnt vmcnt(8)
	s_waitcnt lgkmcnt(0)
	s_barrier
	s_setprio 1
	s_waitcnt lgkmcnt(0)
	v_mfma_i32_16x16x64_i8 v[124:127], v[140:143], v[172:175], v[124:127]
	v_mfma_i32_16x16x64_i8 v[120:123], v[148:151], v[172:175], v[120:123]
	v_mfma_i32_16x16x64_i8 v[116:119], v[140:143], v[188:191], v[116:119]
	v_mfma_i32_16x16x64_i8 v[112:115], v[148:151], v[188:191], v[112:115]
	v_mfma_i32_16x16x64_i8 v[104:107], v[140:143], v[196:199], v[104:107]
	v_mfma_i32_16x16x64_i8 v[96:99], v[148:151], v[196:199], v[96:99]
	v_mfma_i32_16x16x64_i8 v[88:91], v[140:143], v[204:207], v[88:91]
	v_mfma_i32_16x16x64_i8 v[80:83], v[148:151], v[204:207], v[80:83]
	v_mfma_i32_16x16x64_i8 v[124:127], v[144:147], v[176:179], v[124:127]
	v_mfma_i32_16x16x64_i8 v[120:123], v[152:155], v[176:179], v[120:123]
	v_mfma_i32_16x16x64_i8 v[116:119], v[144:147], v[192:195], v[116:119]
	v_mfma_i32_16x16x64_i8 v[112:115], v[152:155], v[192:195], v[112:115]
	v_mfma_i32_16x16x64_i8 v[104:107], v[144:147], v[200:203], v[104:107]
	v_mfma_i32_16x16x64_i8 v[96:99], v[152:155], v[200:203], v[96:99]
	v_mfma_i32_16x16x64_i8 v[88:91], v[144:147], v[208:211], v[88:91]
	v_mfma_i32_16x16x64_i8 v[80:83], v[152:155], v[208:211], v[80:83]
	s_setprio 0
	s_setprio 1
	v_mfma_i32_16x16x64_i8 v[108:111], v[156:159], v[172:175], v[108:111]
	v_mfma_i32_16x16x64_i8 v[100:103], v[164:167], v[172:175], v[100:103]
	v_mfma_i32_16x16x64_i8 v[92:95], v[156:159], v[188:191], v[92:95]
	v_mfma_i32_16x16x64_i8 v[84:87], v[164:167], v[188:191], v[84:87]
	v_mfma_i32_16x16x64_i8 v[76:79], v[156:159], v[196:199], v[76:79]
	v_mfma_i32_16x16x64_i8 v[72:75], v[164:167], v[196:199], v[72:75]
	v_mfma_i32_16x16x64_i8 v[68:71], v[156:159], v[204:207], v[68:71]
	v_mfma_i32_16x16x64_i8 v[64:67], v[164:167], v[204:207], v[64:67]
	v_mfma_i32_16x16x64_i8 v[108:111], v[160:163], v[176:179], v[108:111]
	v_mfma_i32_16x16x64_i8 v[100:103], v[168:171], v[176:179], v[100:103]
	v_mfma_i32_16x16x64_i8 v[92:95], v[160:163], v[192:195], v[92:95]
	v_mfma_i32_16x16x64_i8 v[84:87], v[168:171], v[192:195], v[84:87]
	v_mfma_i32_16x16x64_i8 v[76:79], v[160:163], v[200:203], v[76:79]
	v_mfma_i32_16x16x64_i8 v[72:75], v[168:171], v[200:203], v[72:75]
	v_mfma_i32_16x16x64_i8 v[68:71], v[160:163], v[208:211], v[68:71]
	v_mfma_i32_16x16x64_i8 v[64:67], v[168:171], v[208:211], v[64:67]
	s_setprio 0
	s_barrier
	s_add_u32 s98, s48, s18
	s_addc_u32 s99, s49, s19
	s_add_u32 s100, s50, s18
	s_addc_u32 s101, s51, s19
	s_add_i32 s44, s76, s53
	s_mov_b32 m0, s44
	ds_read_b128 v[172:175], v186 offset:49152
	ds_read_b128 v[176:179], v186 offset:50176
	ds_read_b128 v[188:191], v186 offset:51200
	ds_read_b128 v[192:195], v186 offset:52224
	ds_read_b128 v[196:199], v186 offset:53248
	ds_read_b128 v[200:203], v186 offset:54272
	ds_read_b128 v[204:207], v186 offset:55296
	ds_read_b128 v[208:211], v186 offset:56320
	global_load_lds_dwordx4 v130, s[98:99]
	s_add_i32 m0, s44, 0x2000
	s_add_u32 s44, s48, 0x158080
	s_addc_u32 s45, s49, 0
	s_add_i32 s48, s77, s53
	global_load_lds_dwordx4 v134, s[98:99]
	s_mov_b32 m0, s48
	s_nop 0
	global_load_lds_dwordx4 v130, s[44:45]
	s_add_i32 m0, s48, 0x2000
	s_nop 0
	global_load_lds_dwordx4 v134, s[44:45]
	s_mov_b32 m0, s64
	s_nop 0
	global_load_lds_dwordx4 v128, s[100:101]
	s_mov_b32 m0, s65
	s_nop 0
	global_load_lds_dwordx4 v132, s[100:101]
	s_waitcnt vmcnt(8)
	s_waitcnt lgkmcnt(0)
	s_barrier
	s_setprio 1
	s_waitcnt lgkmcnt(0)
	v_mfma_i32_16x16x64_i8 v[60:63], v[140:143], v[172:175], v[60:63]
	v_mfma_i32_16x16x64_i8 v[56:59], v[148:151], v[172:175], v[56:59]
	v_mfma_i32_16x16x64_i8 v[52:55], v[140:143], v[188:191], v[52:55]
	v_mfma_i32_16x16x64_i8 v[48:51], v[148:151], v[188:191], v[48:51]
	v_mfma_i32_16x16x64_i8 v[40:43], v[140:143], v[196:199], v[40:43]
	v_mfma_i32_16x16x64_i8 v[32:35], v[148:151], v[196:199], v[32:35]
	v_mfma_i32_16x16x64_i8 v[24:27], v[140:143], v[204:207], v[24:27]
	v_mfma_i32_16x16x64_i8 v[16:19], v[148:151], v[204:207], v[16:19]
	v_mfma_i32_16x16x64_i8 v[60:63], v[144:147], v[176:179], v[60:63]
	v_mfma_i32_16x16x64_i8 v[56:59], v[152:155], v[176:179], v[56:59]
	v_mfma_i32_16x16x64_i8 v[52:55], v[144:147], v[192:195], v[52:55]
	v_mfma_i32_16x16x64_i8 v[48:51], v[152:155], v[192:195], v[48:51]
	v_mfma_i32_16x16x64_i8 v[40:43], v[144:147], v[200:203], v[40:43]
	v_mfma_i32_16x16x64_i8 v[32:35], v[152:155], v[200:203], v[32:35]
	v_mfma_i32_16x16x64_i8 v[24:27], v[144:147], v[208:211], v[24:27]
	v_mfma_i32_16x16x64_i8 v[16:19], v[152:155], v[208:211], v[16:19]
	s_setprio 0
	s_setprio 1
	v_mfma_i32_16x16x64_i8 v[44:47], v[156:159], v[172:175], v[44:47]
	v_mfma_i32_16x16x64_i8 v[36:39], v[164:167], v[172:175], v[36:39]
	v_mfma_i32_16x16x64_i8 v[28:31], v[156:159], v[188:191], v[28:31]
	v_mfma_i32_16x16x64_i8 v[20:23], v[164:167], v[188:191], v[20:23]
	v_mfma_i32_16x16x64_i8 v[12:15], v[156:159], v[196:199], v[12:15]
	v_mfma_i32_16x16x64_i8 v[8:11], v[164:167], v[196:199], v[8:11]
	v_mfma_i32_16x16x64_i8 v[4:7], v[156:159], v[204:207], v[4:7]
	v_mfma_i32_16x16x64_i8 v[0:3], v[164:167], v[204:207], v[0:3]
	v_mfma_i32_16x16x64_i8 v[44:47], v[160:163], v[176:179], v[44:47]
	v_mfma_i32_16x16x64_i8 v[36:39], v[168:171], v[176:179], v[36:39]
	v_mfma_i32_16x16x64_i8 v[28:31], v[160:163], v[192:195], v[28:31]
	v_mfma_i32_16x16x64_i8 v[20:23], v[168:171], v[192:195], v[20:23]
	v_mfma_i32_16x16x64_i8 v[12:15], v[160:163], v[200:203], v[12:15]
	v_mfma_i32_16x16x64_i8 v[8:11], v[168:171], v[200:203], v[8:11]
	v_mfma_i32_16x16x64_i8 v[4:7], v[160:163], v[208:211], v[4:7]
	v_mfma_i32_16x16x64_i8 v[0:3], v[168:171], v[208:211], v[0:3]
	s_setprio 0
	s_barrier
	s_add_u32 s73, s73, 0x100
	s_addc_u32 s74, s74, 0
	s_cmp_ge_i32 s75, s71
	s_mov_b64 s[44:45], s[46:47]
	s_mov_b32 s48, s75
	s_cbranch_scc0 .LBB0_1474
	v_cvt_f32_i32_e32 v140, v124
	v_cvt_f32_i32_e32 v141, v125
	v_cvt_f32_i32_e32 v124, v126
	v_cvt_f32_i32_e32 v125, v127
	v_cvt_f32_i32_e32 v142, v120
	v_cvt_f32_i32_e32 v143, v121
	v_cvt_f32_i32_e32 v126, v122
	v_cvt_f32_i32_e32 v127, v123
	v_cvt_f32_i32_e32 v146, v108
	v_cvt_f32_i32_e32 v147, v109
	v_cvt_f32_i32_e32 v120, v110
	v_cvt_f32_i32_e32 v121, v111
	v_cvt_f32_i32_e32 v148, v100
	v_cvt_f32_i32_e32 v149, v101
	v_cvt_f32_i32_e32 v122, v102
	v_cvt_f32_i32_e32 v123, v103
	v_cvt_f32_i32_e32 v144, v116
	v_cvt_f32_i32_e32 v145, v117
	v_cvt_f32_i32_e32 v116, v118
	v_cvt_f32_i32_e32 v117, v119
	v_cvt_f32_i32_e32 v118, v112
	v_cvt_f32_i32_e32 v119, v113
	v_cvt_f32_i32_e32 v112, v114
	v_cvt_f32_i32_e32 v113, v115
	v_cvt_f32_i32_e32 v152, v92
	v_cvt_f32_i32_e32 v153, v93
	v_cvt_f32_i32_e32 v100, v94
	v_cvt_f32_i32_e32 v101, v95
	v_cvt_f32_i32_e32 v156, v84
	v_cvt_f32_i32_e32 v157, v85
	v_cvt_f32_i32_e32 v102, v86
	v_cvt_f32_i32_e32 v103, v87
	v_cvt_f32_i32_e32 v114, v104
	v_cvt_f32_i32_e32 v115, v105
	v_cvt_f32_i32_e32 v86, v106
	v_cvt_f32_i32_e32 v87, v107
	v_cvt_f32_i32_e32 v150, v96
	v_cvt_f32_i32_e32 v151, v97
	v_cvt_f32_i32_e32 v92, v98
	v_cvt_f32_i32_e32 v93, v99
	v_cvt_f32_i32_e32 v160, v76
	v_cvt_f32_i32_e32 v161, v77
	v_cvt_f32_i32_e32 v84, v78
	v_cvt_f32_i32_e32 v85, v79
	v_cvt_f32_i32_e32 v162, v72
	v_cvt_f32_i32_e32 v163, v73
	v_cvt_f32_i32_e32 v94, v74
	v_cvt_f32_i32_e32 v95, v75
	v_cvt_f32_i32_e32 v154, v88
	v_cvt_f32_i32_e32 v155, v89
	v_cvt_f32_i32_e32 v78, v90
	v_cvt_f32_i32_e32 v79, v91
	v_cvt_f32_i32_e32 v158, v80
	v_cvt_f32_i32_e32 v159, v81
	v_cvt_f32_i32_e32 v80, v82
	v_cvt_f32_i32_e32 v81, v83
	v_cvt_f32_i32_e32 v164, v68
	v_cvt_f32_i32_e32 v165, v69
	v_cvt_f32_i32_e32 v76, v70
	v_cvt_f32_i32_e32 v77, v71
	v_cvt_f32_i32_e32 v166, v64
	v_cvt_f32_i32_e32 v167, v65
	v_cvt_f32_i32_e32 v82, v66
	v_cvt_f32_i32_e32 v83, v67
	v_cvt_f32_i32_e32 v70, v60
	v_cvt_f32_i32_e32 v71, v61
	v_cvt_f32_i32_e32 v74, v62
	v_cvt_f32_i32_e32 v75, v63
	v_cvt_f32_i32_e32 v68, v56
	v_cvt_f32_i32_e32 v69, v57
	v_cvt_f32_i32_e32 v72, v58
	v_cvt_f32_i32_e32 v73, v59
	v_cvt_f32_i32_e32 v62, v44
	v_cvt_f32_i32_e32 v63, v45
	v_cvt_f32_i32_e32 v66, v46
	v_cvt_f32_i32_e32 v67, v47
	v_cvt_f32_i32_e32 v60, v36
	v_cvt_f32_i32_e32 v61, v37
	v_cvt_f32_i32_e32 v64, v38
	v_cvt_f32_i32_e32 v65, v39
	v_cvt_f32_i32_e32 v56, v52
	v_cvt_f32_i32_e32 v57, v53
	v_cvt_f32_i32_e32 v58, v54
	v_cvt_f32_i32_e32 v59, v55
	v_cvt_f32_i32_e32 v52, v48
	v_cvt_f32_i32_e32 v53, v49
	v_cvt_f32_i32_e32 v54, v50
	v_cvt_f32_i32_e32 v55, v51
	v_cvt_f32_i32_e32 v46, v28
	v_cvt_f32_i32_e32 v47, v29
	v_cvt_f32_i32_e32 v50, v30
	v_cvt_f32_i32_e32 v51, v31
	v_cvt_f32_i32_e32 v44, v20
	v_cvt_f32_i32_e32 v45, v21
	v_cvt_f32_i32_e32 v48, v22
	v_cvt_f32_i32_e32 v49, v23
	v_cvt_f32_i32_e32 v38, v40
	v_cvt_f32_i32_e32 v39, v41
	v_cvt_f32_i32_e32 v42, v42
	v_cvt_f32_i32_e32 v43, v43
	v_cvt_f32_i32_e32 v36, v32
	v_cvt_f32_i32_e32 v37, v33
	v_cvt_f32_i32_e32 v40, v34
	v_cvt_f32_i32_e32 v41, v35
	v_cvt_f32_i32_e32 v30, v12
	v_cvt_f32_i32_e32 v31, v13
	v_cvt_f32_i32_e32 v34, v14
	v_cvt_f32_i32_e32 v35, v15
	v_cvt_f32_i32_e32 v28, v8
	v_cvt_f32_i32_e32 v29, v9
	v_cvt_f32_i32_e32 v32, v10
	v_cvt_f32_i32_e32 v33, v11
	v_cvt_f32_i32_e32 v22, v24
	v_cvt_f32_i32_e32 v23, v25
	v_cvt_f32_i32_e32 v26, v26
	v_cvt_f32_i32_e32 v27, v27
	v_cvt_f32_i32_e32 v20, v16
	v_cvt_f32_i32_e32 v21, v17
	v_cvt_f32_i32_e32 v24, v18
	v_cvt_f32_i32_e32 v25, v19
	v_cvt_f32_i32_e32 v14, v4
	v_cvt_f32_i32_e32 v15, v5
	v_cvt_f32_i32_e32 v18, v6
	v_cvt_f32_i32_e32 v19, v7
	v_cvt_f32_i32_e32 v12, v0
	v_cvt_f32_i32_e32 v13, v1
	v_cvt_f32_i32_e32 v16, v2
	v_cvt_f32_i32_e32 v17, v3
	s_and_b64 vcc, exec, s[20:21]
	s_cbranch_vccz .LBB0_1477
